# MLA loop: V DMA pieces early in the S0 chain, K DMA pieces among the S1 chain MFMAs
# speedup vs baseline: 1.0043x; 1.0043x over previous
.Lmla_loop:
	ds_read_b128 v[230:233], v193 offset:57344
	ds_read_b128 v[234:237], v186 offset:57344
	ds_read_b128 v[238:241], v187 offset:57344
	ds_read_b128 v[242:245], v188 offset:57344
	s_cmp_lt_u32 s58, s18
	s_cselect_b32 s0, 0, s18
	s_cselect_b32 s1, s6, s13
	s_lshl_b32 s0, s0, 6
	s_sub_i32 s0, s1, s0
	s_add_i32 s0, s51, s0
	s_ashr_i32 s1, s0, 31
	s_lshl_b64 s[10:11], s[0:1], 12
	s_add_u32 s16, s20, s10
	s_addc_u32 s17, s21, s11
	v_exp_f32_e32 v64, v64
	v_exp_f32_e32 v65, v65
	v_add_f32_e32 v212, v64, v212
	v_exp_f32_e32 v66, v66
	v_add_f32_e32 v212, v65, v212
	v_exp_f32_e32 v67, v67
	s_waitcnt lgkmcnt(3)
	v_mfma_f32_32x32x16_bf16 v[80:95], v[230:233], v[124:127], 0
	ds_read_b128 v[230:233], v189 offset:57344
	v_add_f32_e32 v212, v66, v212
	v_exp_f32_e32 v68, v68
	v_add_f32_e32 v212, v67, v212
	v_exp_f32_e32 v69, v69
	s_waitcnt lgkmcnt(3)
	v_mfma_f32_32x32x16_bf16 v[80:95], v[234:237], v[120:123], v[80:95]
	ds_read_b128 v[234:237], v190 offset:57344
	s_cmp_eq_u32 s58, 2
	s_cbranch_scc1 .Lmla_skipv0_o
	s_mov_b32 m0, s54
	v_lshl_add_u64 v[254:255], v[164:165], 1, s[100:101]
	global_load_lds_dwordx4 v[254:255], off
.Lmla_skipv0_o:
	v_add_f32_e32 v212, v68, v212
	v_exp_f32_e32 v70, v70
	v_add_f32_e32 v212, v69, v212
	v_exp_f32_e32 v71, v71
	s_waitcnt lgkmcnt(3)
	v_mfma_f32_32x32x16_bf16 v[80:95], v[238:241], v[116:119], v[80:95]
	ds_read_b128 v[238:241], v191 offset:57344
	v_add_f32_e32 v212, v70, v212
	v_exp_f32_e32 v72, v72
	v_add_f32_e32 v212, v71, v212
	v_exp_f32_e32 v73, v73
	s_waitcnt lgkmcnt(3)
	v_mfma_f32_32x32x16_bf16 v[80:95], v[242:245], v[112:115], v[80:95]
	ds_read_b128 v[242:245], v192 offset:57344
	s_cmp_eq_u32 s58, 2
	s_cbranch_scc1 .Lmla_skipv1_o
	s_mov_b32 m0, s55
	v_lshl_add_u64 v[254:255], v[166:167], 1, s[100:101]
	global_load_lds_dwordx4 v[254:255], off
.Lmla_skipv1_o:
	v_add_f32_e32 v212, v72, v212
	v_exp_f32_e32 v74, v74
	v_add_f32_e32 v212, v73, v212
	v_exp_f32_e32 v75, v75
	s_waitcnt lgkmcnt(3)
	v_mfma_f32_32x32x16_bf16 v[80:95], v[230:233], v[108:111], v[80:95]
	v_add_u32_e32 v211, 0x6000, v203
	ds_read_b128 v[230:233], v211 offset:49152
	v_add_f32_e32 v212, v74, v212
	v_exp_f32_e32 v76, v76
	v_add_f32_e32 v212, v75, v212
	v_exp_f32_e32 v77, v77
	s_waitcnt lgkmcnt(3)
	v_mfma_f32_32x32x16_bf16 v[80:95], v[234:237], v[104:107], v[80:95]
	v_add_u32_e32 v211, 0x6000, v204
	ds_read_b128 v[234:237], v211 offset:49152
	v_add_f32_e32 v212, v76, v212
	v_exp_f32_e32 v78, v78
	v_add_f32_e32 v212, v77, v212
	v_exp_f32_e32 v79, v79
	s_waitcnt lgkmcnt(3)
	v_mfma_f32_32x32x16_bf16 v[80:95], v[238:241], v[100:103], v[80:95]
	v_add_u32_e32 v211, 0x6000, v205
	ds_read_b128 v[238:241], v211 offset:49152
	v_add_f32_e32 v212, v78, v212
	v_add_f32_e32 v212, v79, v212
	v_mov_b32_e32 v213, v212
	s_waitcnt lgkmcnt(3)
	v_mfma_f32_32x32x16_bf16 v[80:95], v[242:245], v[96:99], v[80:95]
	v_add_u32_e32 v211, 0x6000, v206
	ds_read_b128 v[242:245], v211 offset:49152
	v_cvt_pk_bf16_f32 v152, v64, v65
	v_cvt_pk_bf16_f32 v153, v66, v67
	v_cvt_pk_bf16_f32 v154, v68, v69
	s_waitcnt lgkmcnt(3)
	v_mfma_f32_32x32x16_bf16 v[80:95], v[230:233], v[128:131], v[80:95]
	v_add_u32_e32 v211, v209, v194
	ds_read_b128 v[230:233], v211 offset:8192
	v_cvt_pk_bf16_f32 v155, v70, v71
	v_cvt_pk_bf16_f32 v156, v72, v73
	v_cvt_pk_bf16_f32 v157, v74, v75
	s_waitcnt lgkmcnt(3)
	v_mfma_f32_32x32x16_bf16 v[80:95], v[234:237], v[132:135], v[80:95]
	v_add_u32_e32 v211, v209, v195
	ds_read_b128 v[234:237], v211 offset:8192
	v_cvt_pk_bf16_f32 v158, v76, v77
	v_cvt_pk_bf16_f32 v159, v78, v79
	v_permlane32_swap_b32_e32 v212, v213
	s_waitcnt lgkmcnt(3)
	v_mfma_f32_32x32x16_bf16 v[80:95], v[238:241], v[136:139], v[80:95]
	v_add_u32_e32 v211, v209, v196
	ds_read_b128 v[238:241], v211 offset:8192
	v_add_f32_e32 v252, v212, v213
	v_fma_f32 v183, v207, v183, v252
	v_permlane32_swap_b32_e32 v152, v154
	s_waitcnt lgkmcnt(3)
	v_mfma_f32_32x32x16_bf16 v[80:95], v[242:245], v[140:143], v[80:95]
	v_add_u32_e32 v211, v209, v197
	ds_read_b128 v[242:245], v211 offset:8192
	v_permlane32_swap_b32_e32 v153, v155
	v_permlane32_swap_b32_e32 v156, v158
	v_permlane32_swap_b32_e32 v157, v159
	s_waitcnt lgkmcnt(3)
	v_mfma_f32_32x32x16_bf16 v[64:79], v[230:233], v[124:127], 0
	v_add_u32_e32 v211, v209, v198
	ds_read_b128 v[230:233], v211 offset:8192
	s_mov_b32 m0, s23
	v_lshl_add_u64 v[254:255], v[160:161], 1, s[16:17]
	global_load_lds_dwordx4 v[254:255], off
	s_waitcnt lgkmcnt(3)
	v_mfma_f32_32x32x16_bf16 v[64:79], v[234:237], v[120:123], v[64:79]
	v_add_u32_e32 v211, v209, v199
	ds_read_b128 v[234:237], v211 offset:8192
	s_waitcnt lgkmcnt(3)
	v_mfma_f32_32x32x16_bf16 v[64:79], v[238:241], v[116:119], v[64:79]
	v_add_u32_e32 v211, v209, v200
	ds_read_b128 v[238:241], v211 offset:8192
	s_mov_b32 m0, s7
	v_lshl_add_u64 v[254:255], v[162:163], 1, s[16:17]
	global_load_lds_dwordx4 v[254:255], off
	s_waitcnt lgkmcnt(3)
	v_mfma_f32_32x32x16_bf16 v[64:79], v[242:245], v[112:115], v[64:79]
	v_add_u32_e32 v211, v209, v201
	ds_read_b128 v[242:245], v211 offset:8192
	s_waitcnt lgkmcnt(3)
	v_mfma_f32_32x32x16_bf16 v[64:79], v[230:233], v[108:111], v[64:79]
	v_add_u32_e32 v211, 0x6000, v203
	ds_read_b128 v[230:233], v211 offset:53248
	s_mov_b32 m0, s30
	v_mad_i64_i32 v[254:255], s[0:1], s0, v180, v[168:169]
	global_load_lds_dwordx4 v[254:255], off
	s_add_u32 s100, s16, 0x100
	s_addc_u32 s101, s17, 0
	s_waitcnt lgkmcnt(3)
	v_mfma_f32_32x32x16_bf16 v[64:79], v[234:237], v[104:107], v[64:79]
	v_add_u32_e32 v211, 0x6000, v204
	ds_read_b128 v[234:237], v211 offset:53248
	s_waitcnt lgkmcnt(3)
	v_mfma_f32_32x32x16_bf16 v[64:79], v[238:241], v[100:103], v[64:79]
	v_add_u32_e32 v211, 0x6000, v205
	ds_read_b128 v[238:241], v211 offset:53248
	v_max_f32_e32 v249, v80, v81
	v_max3_f32 v249, v249, v82, v83
	s_waitcnt lgkmcnt(3)
	v_mfma_f32_32x32x16_bf16 v[64:79], v[242:245], v[96:99], v[64:79]
	v_add_u32_e32 v211, 0x6000, v206
	ds_read_b128 v[242:245], v211 offset:53248
	v_max3_f32 v249, v249, v84, v85
	v_max3_f32 v249, v249, v86, v87
	s_waitcnt lgkmcnt(3)
	v_mfma_f32_32x32x16_bf16 v[64:79], v[230:233], v[128:131], v[64:79]
	ds_read_b64_tr_b16 v[214:215], v185
	ds_read_b64_tr_b16 v[216:217], v185 offset:2048
	v_max3_f32 v249, v249, v88, v89
	v_max3_f32 v249, v249, v90, v91
	s_waitcnt lgkmcnt(4)
	v_mfma_f32_32x32x16_bf16 v[64:79], v[234:237], v[132:135], v[64:79]
	ds_read_b64_tr_b16 v[218:219], v185 offset:4096
	ds_read_b64_tr_b16 v[220:221], v185 offset:6144
	v_max3_f32 v249, v249, v92, v93
	v_max3_f32 v249, v249, v94, v95
	s_waitcnt lgkmcnt(5)
	v_mfma_f32_32x32x16_bf16 v[64:79], v[238:241], v[136:139], v[64:79]
	ds_read_b64_tr_b16 v[222:223], v185 offset:8192
	ds_read_b64_tr_b16 v[224:225], v185 offset:10240
	s_waitcnt lgkmcnt(6)
	v_mfma_f32_32x32x16_bf16 v[64:79], v[242:245], v[140:143], v[64:79]
	ds_read_b64_tr_b16 v[226:227], v185 offset:12288
	ds_read_b64_tr_b16 v[228:229], v185 offset:14336
	s_waitcnt lgkmcnt(6)
	v_mfma_f32_32x32x16_bf16 v[0:15], v[144:147], v[214:217], v[0:15]
	ds_read_b64_tr_b16 v[214:215], v185 offset:512
	ds_read_b64_tr_b16 v[216:217], v185 offset:2560
	s_waitcnt lgkmcnt(6)
	v_mfma_f32_32x32x16_bf16 v[0:15], v[148:151], v[218:221], v[0:15]
	ds_read_b64_tr_b16 v[218:219], v185 offset:4608
	ds_read_b64_tr_b16 v[220:221], v185 offset:6656
	s_waitcnt lgkmcnt(6)
	v_mfma_f32_32x32x16_bf16 v[0:15], v[152:155], v[222:225], v[0:15]
	ds_read_b64_tr_b16 v[222:223], v185 offset:8704
	ds_read_b64_tr_b16 v[224:225], v185 offset:10752
	s_waitcnt lgkmcnt(6)
	v_mfma_f32_32x32x16_bf16 v[0:15], v[156:159], v[226:229], v[0:15]
	ds_read_b64_tr_b16 v[226:227], v185 offset:12800
	ds_read_b64_tr_b16 v[228:229], v185 offset:14848
	s_waitcnt lgkmcnt(6)
	v_mfma_f32_32x32x16_bf16 v[48:63], v[144:147], v[214:217], v[48:63]
	ds_read_b64_tr_b16 v[214:215], v185 offset:1024
	ds_read_b64_tr_b16 v[216:217], v185 offset:3072
	v_max3_f32 v249, v249, v64, v65
	v_max3_f32 v249, v249, v66, v67
	v_max3_f32 v249, v249, v68, v69
	v_max3_f32 v249, v249, v70, v71
	v_max3_f32 v249, v249, v72, v73
	v_max3_f32 v249, v249, v74, v75
	v_max3_f32 v249, v249, v76, v77
	v_max3_f32 v249, v249, v78, v79
	s_waitcnt lgkmcnt(6)
	v_mfma_f32_32x32x16_bf16 v[48:63], v[148:151], v[218:221], v[48:63]
	ds_read_b64_tr_b16 v[218:219], v185 offset:5120
	ds_read_b64_tr_b16 v[220:221], v185 offset:7168
	v_mov_b32_e32 v250, v249
	s_nop 1
	v_permlane32_swap_b32_e32 v249, v250
	v_max_f32_e32 v249, v249, v250
	v_sub_f32_e32 v250, v249, v208
	v_cmp_ge_f32_e32 vcc, s40, v250
	v_max_f32_e32 v249, v208, v249
	v_sub_f32_e32 v250, v208, v249
	s_waitcnt lgkmcnt(6)
	v_mfma_f32_32x32x16_bf16 v[48:63], v[152:155], v[222:225], v[48:63]
	ds_read_b64_tr_b16 v[222:223], v185 offset:9216
	ds_read_b64_tr_b16 v[224:225], v185 offset:11264
	v_mul_f32_e32 v250, 0x3dd53b94, v250
	v_exp_f32_e32 v250, v250
	s_cmp_eq_u64 vcc, exec
	s_cselect_b64 s[10:11], -1, 0
	v_cndmask_b32_e64 v207, v250, 1.0, s[10:11]
	v_cndmask_b32_e64 v208, v249, v208, s[10:11]
	v_mul_f32_e32 v251, 0xbdd53b94, v208
	v_fmamk_f32 v80, v80, 0x3dd53b94, v251
	s_waitcnt lgkmcnt(6)
	v_mfma_f32_32x32x16_bf16 v[48:63], v[156:159], v[226:229], v[48:63]
	ds_read_b64_tr_b16 v[226:227], v185 offset:13312
	ds_read_b64_tr_b16 v[228:229], v185 offset:15360
	v_fmamk_f32 v81, v81, 0x3dd53b94, v251
	v_fmamk_f32 v82, v82, 0x3dd53b94, v251
	v_fmamk_f32 v83, v83, 0x3dd53b94, v251
	v_fmamk_f32 v84, v84, 0x3dd53b94, v251
	v_fmamk_f32 v85, v85, 0x3dd53b94, v251
	v_fmamk_f32 v86, v86, 0x3dd53b94, v251
	v_fmamk_f32 v87, v87, 0x3dd53b94, v251
	s_waitcnt lgkmcnt(6)
	v_mfma_f32_32x32x16_bf16 v[32:47], v[144:147], v[214:217], v[32:47]
	ds_read_b64_tr_b16 v[214:215], v185 offset:1536
	ds_read_b64_tr_b16 v[216:217], v185 offset:3584
	v_fmamk_f32 v88, v88, 0x3dd53b94, v251
	v_fmamk_f32 v89, v89, 0x3dd53b94, v251
	v_fmamk_f32 v90, v90, 0x3dd53b94, v251
	v_fmamk_f32 v91, v91, 0x3dd53b94, v251
	v_fmamk_f32 v92, v92, 0x3dd53b94, v251
	v_fmamk_f32 v93, v93, 0x3dd53b94, v251
	v_fmamk_f32 v94, v94, 0x3dd53b94, v251
	s_waitcnt lgkmcnt(6)
	v_mfma_f32_32x32x16_bf16 v[32:47], v[148:151], v[218:221], v[32:47]
	ds_read_b64_tr_b16 v[218:219], v185 offset:5632
	ds_read_b64_tr_b16 v[220:221], v185 offset:7680
	v_fmamk_f32 v95, v95, 0x3dd53b94, v251
	v_exp_f32_e32 v80, v80
	v_fmamk_f32 v64, v64, 0x3dd53b94, v251
	v_exp_f32_e32 v81, v81
	v_fmamk_f32 v65, v65, 0x3dd53b94, v251
	v_add_f32_e32 v212, 0, v80
	v_exp_f32_e32 v82, v82
	s_waitcnt lgkmcnt(6)
	v_mfma_f32_32x32x16_bf16 v[32:47], v[152:155], v[222:225], v[32:47]
	ds_read_b64_tr_b16 v[222:223], v185 offset:9728
	ds_read_b64_tr_b16 v[224:225], v185 offset:11776
	v_fmamk_f32 v66, v66, 0x3dd53b94, v251
	v_add_f32_e32 v212, v81, v212
	v_exp_f32_e32 v83, v83
	v_fmamk_f32 v67, v67, 0x3dd53b94, v251
	v_add_f32_e32 v212, v82, v212
	v_exp_f32_e32 v84, v84
	v_fmamk_f32 v68, v68, 0x3dd53b94, v251
	s_waitcnt lgkmcnt(6)
	v_mfma_f32_32x32x16_bf16 v[32:47], v[156:159], v[226:229], v[32:47]
	ds_read_b64_tr_b16 v[226:227], v185 offset:13824
	ds_read_b64_tr_b16 v[228:229], v185 offset:15872
	v_add_f32_e32 v212, v83, v212
	v_exp_f32_e32 v85, v85
	v_fmamk_f32 v69, v69, 0x3dd53b94, v251
	v_add_f32_e32 v212, v84, v212
	v_exp_f32_e32 v86, v86
	v_fmamk_f32 v70, v70, 0x3dd53b94, v251
	v_add_f32_e32 v212, v85, v212
	s_waitcnt lgkmcnt(6)
	v_mfma_f32_32x32x16_bf16 v[16:31], v[144:147], v[214:217], v[16:31]
	v_exp_f32_e32 v87, v87
	v_fmamk_f32 v71, v71, 0x3dd53b94, v251
	v_add_f32_e32 v212, v86, v212
	v_exp_f32_e32 v88, v88
	v_fmamk_f32 v72, v72, 0x3dd53b94, v251
	v_add_f32_e32 v212, v87, v212
	v_exp_f32_e32 v89, v89
	s_waitcnt lgkmcnt(4)
	v_mfma_f32_32x32x16_bf16 v[16:31], v[148:151], v[218:221], v[16:31]
	v_fmamk_f32 v73, v73, 0x3dd53b94, v251
	v_add_f32_e32 v212, v88, v212
	v_exp_f32_e32 v90, v90
	v_fmamk_f32 v74, v74, 0x3dd53b94, v251
	v_add_f32_e32 v212, v89, v212
	v_exp_f32_e32 v91, v91
	v_fmamk_f32 v75, v75, 0x3dd53b94, v251
	s_waitcnt lgkmcnt(2)
	v_mfma_f32_32x32x16_bf16 v[16:31], v[152:155], v[222:225], v[16:31]
	v_add_f32_e32 v212, v90, v212
	v_exp_f32_e32 v92, v92
	v_fmamk_f32 v76, v76, 0x3dd53b94, v251
	v_add_f32_e32 v212, v91, v212
	v_exp_f32_e32 v93, v93
	v_fmamk_f32 v77, v77, 0x3dd53b94, v251
	v_add_f32_e32 v212, v92, v212
	s_waitcnt lgkmcnt(0)
	v_mfma_f32_32x32x16_bf16 v[16:31], v[156:159], v[226:229], v[16:31]
	v_exp_f32_e32 v94, v94
	v_fmamk_f32 v78, v78, 0x3dd53b94, v251
	v_add_f32_e32 v212, v93, v212
	v_exp_f32_e32 v95, v95
	v_fmamk_f32 v79, v79, 0x3dd53b94, v251
	v_add_f32_e32 v212, v94, v212
	v_add_f32_e32 v212, v95, v212
	v_cvt_pk_bf16_f32 v144, v80, v81
	v_cvt_pk_bf16_f32 v145, v82, v83
	v_cvt_pk_bf16_f32 v146, v84, v85
	v_cvt_pk_bf16_f32 v147, v86, v87
	v_cvt_pk_bf16_f32 v148, v88, v89
	v_cvt_pk_bf16_f32 v149, v90, v91
	v_cvt_pk_bf16_f32 v150, v92, v93
	v_cvt_pk_bf16_f32 v151, v94, v95
	v_permlane32_swap_b32_e32 v144, v146
	v_permlane32_swap_b32_e32 v145, v147
	v_permlane32_swap_b32_e32 v148, v150
	v_permlane32_swap_b32_e32 v149, v151
	v_cmp_gt_f32_e32 vcc, 1.0, v207
	s_cbranch_vccz .Lmla_noresc_o
	s_and_saveexec_b64 s[0:1], s[8:9]
	ds_write_b32 v182, v207 offset:128
	s_or_b64 exec, exec, s[0:1]
	s_waitcnt lgkmcnt(0)
	v_add_u32_e32 v253, s50, v181
	ds_read_b128 v[92:95], v253 offset:224
	ds_read_b128 v[88:91], v253 offset:192
	ds_read_b128 v[84:87], v253 offset:160
	ds_read_b128 v[80:83], v253 offset:128
	s_waitcnt lgkmcnt(3)
	v_pk_mul_f32 v[12:13], v[12:13], v[92:93]
	v_pk_mul_f32 v[14:15], v[14:15], v[94:95]
	v_pk_mul_f32 v[60:61], v[60:61], v[92:93]
	v_pk_mul_f32 v[62:63], v[62:63], v[94:95]
	v_pk_mul_f32 v[44:45], v[44:45], v[92:93]
	v_pk_mul_f32 v[46:47], v[46:47], v[94:95]
	v_pk_mul_f32 v[28:29], v[28:29], v[92:93]
	v_pk_mul_f32 v[30:31], v[30:31], v[94:95]
	s_waitcnt lgkmcnt(2)
	v_pk_mul_f32 v[8:9], v[8:9], v[88:89]
	v_pk_mul_f32 v[10:11], v[10:11], v[90:91]
	v_pk_mul_f32 v[56:57], v[56:57], v[88:89]
	v_pk_mul_f32 v[58:59], v[58:59], v[90:91]
	v_pk_mul_f32 v[40:41], v[40:41], v[88:89]
	v_pk_mul_f32 v[42:43], v[42:43], v[90:91]
	v_pk_mul_f32 v[24:25], v[24:25], v[88:89]
	v_pk_mul_f32 v[26:27], v[26:27], v[90:91]
	s_waitcnt lgkmcnt(1)
	v_pk_mul_f32 v[4:5], v[4:5], v[84:85]
	v_pk_mul_f32 v[6:7], v[6:7], v[86:87]
	v_pk_mul_f32 v[52:53], v[52:53], v[84:85]
	v_pk_mul_f32 v[54:55], v[54:55], v[86:87]
	v_pk_mul_f32 v[36:37], v[36:37], v[84:85]
	v_pk_mul_f32 v[38:39], v[38:39], v[86:87]
	v_pk_mul_f32 v[20:21], v[20:21], v[84:85]
	v_pk_mul_f32 v[22:23], v[22:23], v[86:87]
	s_waitcnt lgkmcnt(0)
	v_pk_mul_f32 v[0:1], v[0:1], v[80:81]
	v_pk_mul_f32 v[2:3], v[2:3], v[82:83]
	v_pk_mul_f32 v[48:49], v[48:49], v[80:81]
	v_pk_mul_f32 v[50:51], v[50:51], v[82:83]
	v_pk_mul_f32 v[32:33], v[32:33], v[80:81]
	v_pk_mul_f32 v[34:35], v[34:35], v[82:83]
	v_pk_mul_f32 v[16:17], v[16:17], v[80:81]
	v_pk_mul_f32 v[18:19], v[18:19], v[82:83]
.Lmla_noresc_o:
	s_add_i32 s58, s58, 1
	s_waitcnt vmcnt(0) lgkmcnt(0)
	s_barrier
	ds_read_b128 v[230:233], v193 offset:32768
	ds_read_b128 v[234:237], v186 offset:32768
	ds_read_b128 v[238:241], v187 offset:32768
	ds_read_b128 v[242:245], v188 offset:32768
	s_cmp_lt_u32 s58, s18
	s_cselect_b32 s0, 0, s18
	s_cselect_b32 s1, s6, s13
	s_lshl_b32 s0, s0, 6
	s_sub_i32 s0, s1, s0
	s_add_i32 s0, s51, s0
	s_add_i32 s0, s0, 64
	s_ashr_i32 s1, s0, 31
	s_lshl_b64 s[10:11], s[0:1], 12
	s_add_u32 s16, s20, s10
	s_addc_u32 s17, s21, s11
	v_exp_f32_e32 v64, v64
	v_exp_f32_e32 v65, v65
	v_add_f32_e32 v212, v64, v212
	v_exp_f32_e32 v66, v66
	v_add_f32_e32 v212, v65, v212
	v_exp_f32_e32 v67, v67
	s_waitcnt lgkmcnt(3)
	v_mfma_f32_32x32x16_bf16 v[80:95], v[230:233], v[124:127], 0
	ds_read_b128 v[230:233], v189 offset:32768
	v_add_f32_e32 v212, v66, v212
	v_exp_f32_e32 v68, v68
	v_add_f32_e32 v212, v67, v212
	v_exp_f32_e32 v69, v69
	s_waitcnt lgkmcnt(3)
	v_mfma_f32_32x32x16_bf16 v[80:95], v[234:237], v[120:123], v[80:95]
	ds_read_b128 v[234:237], v190 offset:32768
	s_mov_b32 m0, s22
	v_lshl_add_u64 v[254:255], v[164:165], 1, s[100:101]
	global_load_lds_dwordx4 v[254:255], off
	v_add_f32_e32 v212, v68, v212
	v_exp_f32_e32 v70, v70
	v_add_f32_e32 v212, v69, v212
	v_exp_f32_e32 v71, v71
	s_waitcnt lgkmcnt(3)
	v_mfma_f32_32x32x16_bf16 v[80:95], v[238:241], v[116:119], v[80:95]
	ds_read_b128 v[238:241], v191 offset:32768
	v_add_f32_e32 v212, v70, v212
	v_exp_f32_e32 v72, v72
	v_add_f32_e32 v212, v71, v212
	v_exp_f32_e32 v73, v73
	s_waitcnt lgkmcnt(3)
	v_mfma_f32_32x32x16_bf16 v[80:95], v[242:245], v[112:115], v[80:95]
	ds_read_b128 v[242:245], v192 offset:32768
	s_mov_b32 m0, s31
	v_lshl_add_u64 v[254:255], v[166:167], 1, s[100:101]
	global_load_lds_dwordx4 v[254:255], off
	v_add_f32_e32 v212, v72, v212
	v_exp_f32_e32 v74, v74
	v_add_f32_e32 v212, v73, v212
	v_exp_f32_e32 v75, v75
	s_waitcnt lgkmcnt(3)
	v_mfma_f32_32x32x16_bf16 v[80:95], v[230:233], v[108:111], v[80:95]
	ds_read_b128 v[230:233], v203 offset:49152
	v_add_f32_e32 v212, v74, v212
	v_exp_f32_e32 v76, v76
	v_add_f32_e32 v212, v75, v212
	v_exp_f32_e32 v77, v77
	s_waitcnt lgkmcnt(3)
	v_mfma_f32_32x32x16_bf16 v[80:95], v[234:237], v[104:107], v[80:95]
	ds_read_b128 v[234:237], v204 offset:49152
	v_add_f32_e32 v212, v76, v212
	v_exp_f32_e32 v78, v78
	v_add_f32_e32 v212, v77, v212
	v_exp_f32_e32 v79, v79
	s_waitcnt lgkmcnt(3)
	v_mfma_f32_32x32x16_bf16 v[80:95], v[238:241], v[100:103], v[80:95]
	ds_read_b128 v[238:241], v205 offset:49152
	v_add_f32_e32 v212, v78, v212
	v_add_f32_e32 v212, v79, v212
	v_mov_b32_e32 v213, v212
	s_waitcnt lgkmcnt(3)
	v_mfma_f32_32x32x16_bf16 v[80:95], v[242:245], v[96:99], v[80:95]
	ds_read_b128 v[242:245], v206 offset:49152
	v_cvt_pk_bf16_f32 v152, v64, v65
	v_cvt_pk_bf16_f32 v153, v66, v67
	v_cvt_pk_bf16_f32 v154, v68, v69
	s_waitcnt lgkmcnt(3)
	v_mfma_f32_32x32x16_bf16 v[80:95], v[230:233], v[128:131], v[80:95]
	ds_read_b128 v[230:233], v193 offset:40960
	v_cvt_pk_bf16_f32 v155, v70, v71
	v_cvt_pk_bf16_f32 v156, v72, v73
	v_cvt_pk_bf16_f32 v157, v74, v75
	s_waitcnt lgkmcnt(3)
	v_mfma_f32_32x32x16_bf16 v[80:95], v[234:237], v[132:135], v[80:95]
	ds_read_b128 v[234:237], v186 offset:40960
	v_cvt_pk_bf16_f32 v158, v76, v77
	v_cvt_pk_bf16_f32 v159, v78, v79
	v_permlane32_swap_b32_e32 v212, v213
	s_waitcnt lgkmcnt(3)
	v_mfma_f32_32x32x16_bf16 v[80:95], v[238:241], v[136:139], v[80:95]
	ds_read_b128 v[238:241], v187 offset:40960
	v_add_f32_e32 v252, v212, v213
	v_fma_f32 v183, v207, v183, v252
	v_permlane32_swap_b32_e32 v152, v154
	s_waitcnt lgkmcnt(3)
	v_mfma_f32_32x32x16_bf16 v[80:95], v[242:245], v[140:143], v[80:95]
	ds_read_b128 v[242:245], v188 offset:40960
	v_permlane32_swap_b32_e32 v153, v155
	v_permlane32_swap_b32_e32 v156, v158
	v_permlane32_swap_b32_e32 v157, v159
	s_waitcnt lgkmcnt(3)
	v_mfma_f32_32x32x16_bf16 v[64:79], v[230:233], v[124:127], 0
	ds_read_b128 v[230:233], v189 offset:40960
	s_mov_b32 m0, s44
	v_lshl_add_u64 v[254:255], v[160:161], 1, s[16:17]
	global_load_lds_dwordx4 v[254:255], off
	s_waitcnt lgkmcnt(3)
	v_mfma_f32_32x32x16_bf16 v[64:79], v[234:237], v[120:123], v[64:79]
	ds_read_b128 v[234:237], v190 offset:40960
	s_waitcnt lgkmcnt(3)
	v_mfma_f32_32x32x16_bf16 v[64:79], v[238:241], v[116:119], v[64:79]
	ds_read_b128 v[238:241], v191 offset:40960
	s_mov_b32 m0, s45
	v_lshl_add_u64 v[254:255], v[162:163], 1, s[16:17]
	global_load_lds_dwordx4 v[254:255], off
	s_waitcnt lgkmcnt(3)
	v_mfma_f32_32x32x16_bf16 v[64:79], v[242:245], v[112:115], v[64:79]
	ds_read_b128 v[242:245], v192 offset:40960
	s_waitcnt lgkmcnt(3)
	v_mfma_f32_32x32x16_bf16 v[64:79], v[230:233], v[108:111], v[64:79]
	ds_read_b128 v[230:233], v203 offset:53248
	s_mov_b32 m0, s49
	v_mad_i64_i32 v[254:255], s[0:1], s0, v180, v[168:169]
	global_load_lds_dwordx4 v[254:255], off
	s_add_u32 s100, s16, 0x100
	s_addc_u32 s101, s17, 0
	s_waitcnt lgkmcnt(3)
	v_mfma_f32_32x32x16_bf16 v[64:79], v[234:237], v[104:107], v[64:79]
	ds_read_b128 v[234:237], v204 offset:53248
	s_waitcnt lgkmcnt(3)
	v_mfma_f32_32x32x16_bf16 v[64:79], v[238:241], v[100:103], v[64:79]
	ds_read_b128 v[238:241], v205 offset:53248
	v_max_f32_e32 v249, v80, v81
	v_max3_f32 v249, v249, v82, v83
	s_waitcnt lgkmcnt(3)
	v_mfma_f32_32x32x16_bf16 v[64:79], v[242:245], v[96:99], v[64:79]
	ds_read_b128 v[242:245], v206 offset:53248
	v_max3_f32 v249, v249, v84, v85
	v_max3_f32 v249, v249, v86, v87
	s_waitcnt lgkmcnt(3)
	v_mfma_f32_32x32x16_bf16 v[64:79], v[230:233], v[128:131], v[64:79]
	ds_read_b64_tr_b16 v[214:215], v184
	ds_read_b64_tr_b16 v[216:217], v184 offset:2048
	v_max3_f32 v249, v249, v88, v89
	v_max3_f32 v249, v249, v90, v91
	s_waitcnt lgkmcnt(4)
	v_mfma_f32_32x32x16_bf16 v[64:79], v[234:237], v[132:135], v[64:79]
	ds_read_b64_tr_b16 v[218:219], v184 offset:4096
	ds_read_b64_tr_b16 v[220:221], v184 offset:6144
	v_max3_f32 v249, v249, v92, v93
	v_max3_f32 v249, v249, v94, v95
	s_waitcnt lgkmcnt(5)
	v_mfma_f32_32x32x16_bf16 v[64:79], v[238:241], v[136:139], v[64:79]
	ds_read_b64_tr_b16 v[222:223], v184 offset:8192
	ds_read_b64_tr_b16 v[224:225], v184 offset:10240
	s_waitcnt lgkmcnt(6)
	v_mfma_f32_32x32x16_bf16 v[64:79], v[242:245], v[140:143], v[64:79]
	ds_read_b64_tr_b16 v[226:227], v184 offset:12288
	ds_read_b64_tr_b16 v[228:229], v184 offset:14336
	s_waitcnt lgkmcnt(6)
	v_mfma_f32_32x32x16_bf16 v[0:15], v[144:147], v[214:217], v[0:15]
	ds_read_b64_tr_b16 v[214:215], v184 offset:512
	ds_read_b64_tr_b16 v[216:217], v184 offset:2560
	s_waitcnt lgkmcnt(6)
	v_mfma_f32_32x32x16_bf16 v[0:15], v[148:151], v[218:221], v[0:15]
	ds_read_b64_tr_b16 v[218:219], v184 offset:4608
	ds_read_b64_tr_b16 v[220:221], v184 offset:6656
	s_waitcnt lgkmcnt(6)
	v_mfma_f32_32x32x16_bf16 v[0:15], v[152:155], v[222:225], v[0:15]
	ds_read_b64_tr_b16 v[222:223], v184 offset:8704
	ds_read_b64_tr_b16 v[224:225], v184 offset:10752
	s_waitcnt lgkmcnt(6)
	v_mfma_f32_32x32x16_bf16 v[0:15], v[156:159], v[226:229], v[0:15]
	ds_read_b64_tr_b16 v[226:227], v184 offset:12800
	ds_read_b64_tr_b16 v[228:229], v184 offset:14848
	s_waitcnt lgkmcnt(6)
	v_mfma_f32_32x32x16_bf16 v[48:63], v[144:147], v[214:217], v[48:63]
	ds_read_b64_tr_b16 v[214:215], v184 offset:1024
	ds_read_b64_tr_b16 v[216:217], v184 offset:3072
	v_max3_f32 v249, v249, v64, v65
	v_max3_f32 v249, v249, v66, v67
	v_max3_f32 v249, v249, v68, v69
	v_max3_f32 v249, v249, v70, v71
	v_max3_f32 v249, v249, v72, v73
	v_max3_f32 v249, v249, v74, v75
	v_max3_f32 v249, v249, v76, v77
	v_max3_f32 v249, v249, v78, v79
	s_waitcnt lgkmcnt(6)
	v_mfma_f32_32x32x16_bf16 v[48:63], v[148:151], v[218:221], v[48:63]
	ds_read_b64_tr_b16 v[218:219], v184 offset:5120
	ds_read_b64_tr_b16 v[220:221], v184 offset:7168
	v_mov_b32_e32 v250, v249
	s_nop 1
	v_permlane32_swap_b32_e32 v249, v250
	v_max_f32_e32 v249, v249, v250
	v_sub_f32_e32 v250, v249, v208
	v_cmp_ge_f32_e32 vcc, s40, v250
	v_max_f32_e32 v249, v208, v249
	v_sub_f32_e32 v250, v208, v249
	s_waitcnt lgkmcnt(6)
	v_mfma_f32_32x32x16_bf16 v[48:63], v[152:155], v[222:225], v[48:63]
	ds_read_b64_tr_b16 v[222:223], v184 offset:9216
	ds_read_b64_tr_b16 v[224:225], v184 offset:11264
	v_mul_f32_e32 v250, 0x3dd53b94, v250
	v_exp_f32_e32 v250, v250
	s_cmp_eq_u64 vcc, exec
	s_cselect_b64 s[10:11], -1, 0
	v_cndmask_b32_e64 v207, v250, 1.0, s[10:11]
	v_cndmask_b32_e64 v208, v249, v208, s[10:11]
	v_mul_f32_e32 v251, 0xbdd53b94, v208
	v_fmamk_f32 v80, v80, 0x3dd53b94, v251
	s_waitcnt lgkmcnt(6)
	v_mfma_f32_32x32x16_bf16 v[48:63], v[156:159], v[226:229], v[48:63]
	ds_read_b64_tr_b16 v[226:227], v184 offset:13312
	ds_read_b64_tr_b16 v[228:229], v184 offset:15360
	v_fmamk_f32 v81, v81, 0x3dd53b94, v251
	v_fmamk_f32 v82, v82, 0x3dd53b94, v251
	v_fmamk_f32 v83, v83, 0x3dd53b94, v251
	v_fmamk_f32 v84, v84, 0x3dd53b94, v251
	v_fmamk_f32 v85, v85, 0x3dd53b94, v251
	v_fmamk_f32 v86, v86, 0x3dd53b94, v251
	v_fmamk_f32 v87, v87, 0x3dd53b94, v251
	s_waitcnt lgkmcnt(6)
	v_mfma_f32_32x32x16_bf16 v[32:47], v[144:147], v[214:217], v[32:47]
	ds_read_b64_tr_b16 v[214:215], v184 offset:1536
	ds_read_b64_tr_b16 v[216:217], v184 offset:3584
	v_fmamk_f32 v88, v88, 0x3dd53b94, v251
	v_fmamk_f32 v89, v89, 0x3dd53b94, v251
	v_fmamk_f32 v90, v90, 0x3dd53b94, v251
	v_fmamk_f32 v91, v91, 0x3dd53b94, v251
	v_fmamk_f32 v92, v92, 0x3dd53b94, v251
	v_fmamk_f32 v93, v93, 0x3dd53b94, v251
	v_fmamk_f32 v94, v94, 0x3dd53b94, v251
	s_waitcnt lgkmcnt(6)
	v_mfma_f32_32x32x16_bf16 v[32:47], v[148:151], v[218:221], v[32:47]
	ds_read_b64_tr_b16 v[218:219], v184 offset:5632
	ds_read_b64_tr_b16 v[220:221], v184 offset:7680
	v_fmamk_f32 v95, v95, 0x3dd53b94, v251
	v_exp_f32_e32 v80, v80
	v_fmamk_f32 v64, v64, 0x3dd53b94, v251
	v_exp_f32_e32 v81, v81
	v_fmamk_f32 v65, v65, 0x3dd53b94, v251
	v_add_f32_e32 v212, 0, v80
	v_exp_f32_e32 v82, v82
	s_waitcnt lgkmcnt(6)
	v_mfma_f32_32x32x16_bf16 v[32:47], v[152:155], v[222:225], v[32:47]
	ds_read_b64_tr_b16 v[222:223], v184 offset:9728
	ds_read_b64_tr_b16 v[224:225], v184 offset:11776
	v_fmamk_f32 v66, v66, 0x3dd53b94, v251
	v_add_f32_e32 v212, v81, v212
	v_exp_f32_e32 v83, v83
	v_fmamk_f32 v67, v67, 0x3dd53b94, v251
	v_add_f32_e32 v212, v82, v212
	v_exp_f32_e32 v84, v84
	v_fmamk_f32 v68, v68, 0x3dd53b94, v251
	s_waitcnt lgkmcnt(6)
	v_mfma_f32_32x32x16_bf16 v[32:47], v[156:159], v[226:229], v[32:47]
	ds_read_b64_tr_b16 v[226:227], v184 offset:13824
	ds_read_b64_tr_b16 v[228:229], v184 offset:15872
	v_add_f32_e32 v212, v83, v212
	v_exp_f32_e32 v85, v85
	v_fmamk_f32 v69, v69, 0x3dd53b94, v251
	v_add_f32_e32 v212, v84, v212
	v_exp_f32_e32 v86, v86
	v_fmamk_f32 v70, v70, 0x3dd53b94, v251
	v_add_f32_e32 v212, v85, v212
	s_waitcnt lgkmcnt(6)
	v_mfma_f32_32x32x16_bf16 v[16:31], v[144:147], v[214:217], v[16:31]
	v_exp_f32_e32 v87, v87
	v_fmamk_f32 v71, v71, 0x3dd53b94, v251
	v_add_f32_e32 v212, v86, v212
	v_exp_f32_e32 v88, v88
	v_fmamk_f32 v72, v72, 0x3dd53b94, v251
	v_add_f32_e32 v212, v87, v212
	v_exp_f32_e32 v89, v89
	s_waitcnt lgkmcnt(4)
	v_mfma_f32_32x32x16_bf16 v[16:31], v[148:151], v[218:221], v[16:31]
	v_fmamk_f32 v73, v73, 0x3dd53b94, v251
	v_add_f32_e32 v212, v88, v212
	v_exp_f32_e32 v90, v90
	v_fmamk_f32 v74, v74, 0x3dd53b94, v251
	v_add_f32_e32 v212, v89, v212
	v_exp_f32_e32 v91, v91
	v_fmamk_f32 v75, v75, 0x3dd53b94, v251
	s_waitcnt lgkmcnt(2)
	v_mfma_f32_32x32x16_bf16 v[16:31], v[152:155], v[222:225], v[16:31]
	v_add_f32_e32 v212, v90, v212
	v_exp_f32_e32 v92, v92
	v_fmamk_f32 v76, v76, 0x3dd53b94, v251
	v_add_f32_e32 v212, v91, v212
	v_exp_f32_e32 v93, v93
	v_fmamk_f32 v77, v77, 0x3dd53b94, v251
	v_add_f32_e32 v212, v92, v212
	s_waitcnt lgkmcnt(0)
	v_mfma_f32_32x32x16_bf16 v[16:31], v[156:159], v[226:229], v[16:31]
	v_exp_f32_e32 v94, v94
	v_fmamk_f32 v78, v78, 0x3dd53b94, v251
	v_add_f32_e32 v212, v93, v212
	v_exp_f32_e32 v95, v95
	v_fmamk_f32 v79, v79, 0x3dd53b94, v251
	v_add_f32_e32 v212, v94, v212
	v_add_f32_e32 v212, v95, v212
	v_cvt_pk_bf16_f32 v144, v80, v81
	v_cvt_pk_bf16_f32 v145, v82, v83
	v_cvt_pk_bf16_f32 v146, v84, v85
	v_cvt_pk_bf16_f32 v147, v86, v87
	v_cvt_pk_bf16_f32 v148, v88, v89
	v_cvt_pk_bf16_f32 v149, v90, v91
	v_cvt_pk_bf16_f32 v150, v92, v93
	v_cvt_pk_bf16_f32 v151, v94, v95
	v_permlane32_swap_b32_e32 v144, v146
	v_permlane32_swap_b32_e32 v145, v147
	v_permlane32_swap_b32_e32 v148, v150
	v_permlane32_swap_b32_e32 v149, v151
	v_cmp_gt_f32_e32 vcc, 1.0, v207
	s_cbranch_vccz .Lmla_noresc_e
	s_and_saveexec_b64 s[0:1], s[8:9]
	ds_write_b32 v182, v207 offset:128
	s_or_b64 exec, exec, s[0:1]
	s_waitcnt lgkmcnt(0)
	v_add_u32_e32 v253, s50, v181
	ds_read_b128 v[92:95], v253 offset:224
	ds_read_b128 v[88:91], v253 offset:192
	ds_read_b128 v[84:87], v253 offset:160
	ds_read_b128 v[80:83], v253 offset:128
	s_waitcnt lgkmcnt(3)
	v_pk_mul_f32 v[12:13], v[12:13], v[92:93]
	v_pk_mul_f32 v[14:15], v[14:15], v[94:95]
	v_pk_mul_f32 v[60:61], v[60:61], v[92:93]
	v_pk_mul_f32 v[62:63], v[62:63], v[94:95]
	v_pk_mul_f32 v[44:45], v[44:45], v[92:93]
	v_pk_mul_f32 v[46:47], v[46:47], v[94:95]
	v_pk_mul_f32 v[28:29], v[28:29], v[92:93]
	v_pk_mul_f32 v[30:31], v[30:31], v[94:95]
	s_waitcnt lgkmcnt(2)
	v_pk_mul_f32 v[8:9], v[8:9], v[88:89]
	v_pk_mul_f32 v[10:11], v[10:11], v[90:91]
	v_pk_mul_f32 v[56:57], v[56:57], v[88:89]
	v_pk_mul_f32 v[58:59], v[58:59], v[90:91]
	v_pk_mul_f32 v[40:41], v[40:41], v[88:89]
	v_pk_mul_f32 v[42:43], v[42:43], v[90:91]
	v_pk_mul_f32 v[24:25], v[24:25], v[88:89]
	v_pk_mul_f32 v[26:27], v[26:27], v[90:91]
	s_waitcnt lgkmcnt(1)
	v_pk_mul_f32 v[4:5], v[4:5], v[84:85]
	v_pk_mul_f32 v[6:7], v[6:7], v[86:87]
	v_pk_mul_f32 v[52:53], v[52:53], v[84:85]
	v_pk_mul_f32 v[54:55], v[54:55], v[86:87]
	v_pk_mul_f32 v[36:37], v[36:37], v[84:85]
	v_pk_mul_f32 v[38:39], v[38:39], v[86:87]
	v_pk_mul_f32 v[20:21], v[20:21], v[84:85]
	v_pk_mul_f32 v[22:23], v[22:23], v[86:87]
	s_waitcnt lgkmcnt(0)
	v_pk_mul_f32 v[0:1], v[0:1], v[80:81]
	v_pk_mul_f32 v[2:3], v[2:3], v[82:83]
	v_pk_mul_f32 v[48:49], v[48:49], v[80:81]
	v_pk_mul_f32 v[50:51], v[50:51], v[82:83]
	v_pk_mul_f32 v[32:33], v[32:33], v[80:81]
	v_pk_mul_f32 v[34:35], v[34:35], v[82:83]
	v_pk_mul_f32 v[16:17], v[16:17], v[80:81]
	v_pk_mul_f32 v[18:19], v[18:19], v[82:83]
.Lmla_noresc_e:
	s_add_i32 s58, s58, 1
	s_addk_i32 s51, 0x80
	s_waitcnt vmcnt(0) lgkmcnt(0)
	s_barrier
	s_cmp_ge_u32 s58, s19
	s_cbranch_scc0 .Lmla_loop
	ds_read_b128 v[230:233], v193 offset:57344
	ds_read_b128 v[234:237], v186 offset:57344
	ds_read_b128 v[238:241], v187 offset:57344
	ds_read_b128 v[242:245], v188 offset:57344
	v_exp_f32_e32 v64, v64
	v_exp_f32_e32 v65, v65
	v_add_f32_e32 v212, v64, v212
	v_exp_f32_e32 v66, v66
	v_add_f32_e32 v212, v65, v212
	v_exp_f32_e32 v67, v67
	s_waitcnt lgkmcnt(3)
	v_mfma_f32_32x32x16_bf16 v[80:95], v[230:233], v[124:127], 0
	ds_read_b128 v[230:233], v189 offset:57344
	v_add_f32_e32 v212, v66, v212
	v_exp_f32_e32 v68, v68
	v_add_f32_e32 v212, v67, v212
	v_exp_f32_e32 v69, v69
	s_waitcnt lgkmcnt(3)
	v_mfma_f32_32x32x16_bf16 v[80:95], v[234:237], v[120:123], v[80:95]
	ds_read_b128 v[234:237], v190 offset:57344
	s_mov_b32 m0, s54
	v_lshl_add_u64 v[254:255], v[164:165], 1, s[100:101]
	global_load_lds_dwordx4 v[254:255], off
	v_add_f32_e32 v212, v68, v212
	v_exp_f32_e32 v70, v70
	v_add_f32_e32 v212, v69, v212
	v_exp_f32_e32 v71, v71
	s_waitcnt lgkmcnt(3)
	v_mfma_f32_32x32x16_bf16 v[80:95], v[238:241], v[116:119], v[80:95]
	ds_read_b128 v[238:241], v191 offset:57344
	v_add_f32_e32 v212, v70, v212
	v_exp_f32_e32 v72, v72
	v_add_f32_e32 v212, v71, v212
	v_exp_f32_e32 v73, v73
	s_waitcnt lgkmcnt(3)
	v_mfma_f32_32x32x16_bf16 v[80:95], v[242:245], v[112:115], v[80:95]
	ds_read_b128 v[242:245], v192 offset:57344
	s_mov_b32 m0, s55
	v_lshl_add_u64 v[254:255], v[166:167], 1, s[100:101]
	global_load_lds_dwordx4 v[254:255], off
	v_add_f32_e32 v212, v72, v212
	v_exp_f32_e32 v74, v74
	v_add_f32_e32 v212, v73, v212
	v_exp_f32_e32 v75, v75
	s_waitcnt lgkmcnt(3)
	v_mfma_f32_32x32x16_bf16 v[80:95], v[230:233], v[108:111], v[80:95]
	v_add_u32_e32 v211, 0x6000, v203
	ds_read_b128 v[230:233], v211 offset:49152
	v_add_f32_e32 v212, v74, v212
	v_exp_f32_e32 v76, v76
	v_add_f32_e32 v212, v75, v212
	v_exp_f32_e32 v77, v77
	s_waitcnt lgkmcnt(3)
	v_mfma_f32_32x32x16_bf16 v[80:95], v[234:237], v[104:107], v[80:95]
	v_add_u32_e32 v211, 0x6000, v204
	ds_read_b128 v[234:237], v211 offset:49152
	v_add_f32_e32 v212, v76, v212
	v_exp_f32_e32 v78, v78
	v_add_f32_e32 v212, v77, v212
	v_exp_f32_e32 v79, v79
	s_waitcnt lgkmcnt(3)
	v_mfma_f32_32x32x16_bf16 v[80:95], v[238:241], v[100:103], v[80:95]
	v_add_u32_e32 v211, 0x6000, v205
	ds_read_b128 v[238:241], v211 offset:49152
	v_add_f32_e32 v212, v78, v212
	v_add_f32_e32 v212, v79, v212
	v_mov_b32_e32 v213, v212
	s_waitcnt lgkmcnt(3)
	v_mfma_f32_32x32x16_bf16 v[80:95], v[242:245], v[96:99], v[80:95]
	v_add_u32_e32 v211, 0x6000, v206
	ds_read_b128 v[242:245], v211 offset:49152
	v_cvt_pk_bf16_f32 v152, v64, v65
	v_cvt_pk_bf16_f32 v153, v66, v67
	v_cvt_pk_bf16_f32 v154, v68, v69
	s_waitcnt lgkmcnt(3)
	v_mfma_f32_32x32x16_bf16 v[80:95], v[230:233], v[128:131], v[80:95]
	v_add_u32_e32 v211, v209, v194
	ds_read_b128 v[230:233], v211 offset:8192
	v_cvt_pk_bf16_f32 v155, v70, v71
	v_cvt_pk_bf16_f32 v156, v72, v73
	v_cvt_pk_bf16_f32 v157, v74, v75
	s_waitcnt lgkmcnt(3)
	v_mfma_f32_32x32x16_bf16 v[80:95], v[234:237], v[132:135], v[80:95]
	v_add_u32_e32 v211, v209, v195
	ds_read_b128 v[234:237], v211 offset:8192
	v_cvt_pk_bf16_f32 v158, v76, v77
	v_cvt_pk_bf16_f32 v159, v78, v79
	v_permlane32_swap_b32_e32 v212, v213
	s_waitcnt lgkmcnt(3)
	v_mfma_f32_32x32x16_bf16 v[80:95], v[238:241], v[136:139], v[80:95]
	v_add_u32_e32 v211, v209, v196
	ds_read_b128 v[238:241], v211 offset:8192
	v_add_f32_e32 v252, v212, v213
	v_fma_f32 v183, v207, v183, v252
	v_permlane32_swap_b32_e32 v152, v154
	s_waitcnt lgkmcnt(3)
	v_mfma_f32_32x32x16_bf16 v[80:95], v[242:245], v[140:143], v[80:95]
	v_add_u32_e32 v211, v209, v197
	ds_read_b128 v[242:245], v211 offset:8192
	v_permlane32_swap_b32_e32 v153, v155
	v_permlane32_swap_b32_e32 v156, v158
	v_permlane32_swap_b32_e32 v157, v159
	s_waitcnt lgkmcnt(3)
	v_mfma_f32_32x32x16_bf16 v[64:79], v[230:233], v[124:127], 0
	v_add_u32_e32 v211, v209, v198
	ds_read_b128 v[230:233], v211 offset:8192
	s_waitcnt lgkmcnt(3)
	v_mfma_f32_32x32x16_bf16 v[64:79], v[234:237], v[120:123], v[64:79]
	v_add_u32_e32 v211, v209, v199
	ds_read_b128 v[234:237], v211 offset:8192
	s_waitcnt lgkmcnt(3)
	v_mfma_f32_32x32x16_bf16 v[64:79], v[238:241], v[116:119], v[64:79]
	v_add_u32_e32 v211, v209, v200
	ds_read_b128 v[238:241], v211 offset:8192
	s_waitcnt lgkmcnt(3)
	v_mfma_f32_32x32x16_bf16 v[64:79], v[242:245], v[112:115], v[64:79]
	v_add_u32_e32 v211, v209, v201
	ds_read_b128 v[242:245], v211 offset:8192
	s_waitcnt lgkmcnt(3)
	v_mfma_f32_32x32x16_bf16 v[64:79], v[230:233], v[108:111], v[64:79]
	v_add_u32_e32 v211, 0x6000, v203
	ds_read_b128 v[230:233], v211 offset:53248
	s_waitcnt lgkmcnt(3)
	v_mfma_f32_32x32x16_bf16 v[64:79], v[234:237], v[104:107], v[64:79]
	v_add_u32_e32 v211, 0x6000, v204
	ds_read_b128 v[234:237], v211 offset:53248
	s_waitcnt lgkmcnt(3)
	v_mfma_f32_32x32x16_bf16 v[64:79], v[238:241], v[100:103], v[64:79]
	v_add_u32_e32 v211, 0x6000, v205
	ds_read_b128 v[238:241], v211 offset:53248
	v_max_f32_e32 v249, v80, v81
	v_max3_f32 v249, v249, v82, v83
	s_waitcnt lgkmcnt(3)
	v_mfma_f32_32x32x16_bf16 v[64:79], v[242:245], v[96:99], v[64:79]
	v_add_u32_e32 v211, 0x6000, v206
	ds_read_b128 v[242:245], v211 offset:53248
	v_max3_f32 v249, v249, v84, v85
	v_max3_f32 v249, v249, v86, v87
	s_waitcnt lgkmcnt(3)
	v_mfma_f32_32x32x16_bf16 v[64:79], v[230:233], v[128:131], v[64:79]
	ds_read_b64_tr_b16 v[214:215], v185
	ds_read_b64_tr_b16 v[216:217], v185 offset:2048
	v_max3_f32 v249, v249, v88, v89
	v_max3_f32 v249, v249, v90, v91
	s_waitcnt lgkmcnt(4)
	v_mfma_f32_32x32x16_bf16 v[64:79], v[234:237], v[132:135], v[64:79]
	ds_read_b64_tr_b16 v[218:219], v185 offset:4096
	ds_read_b64_tr_b16 v[220:221], v185 offset:6144
	v_max3_f32 v249, v249, v92, v93
	v_max3_f32 v249, v249, v94, v95
	s_waitcnt lgkmcnt(5)
	v_mfma_f32_32x32x16_bf16 v[64:79], v[238:241], v[136:139], v[64:79]
	ds_read_b64_tr_b16 v[222:223], v185 offset:8192
	ds_read_b64_tr_b16 v[224:225], v185 offset:10240
	s_waitcnt lgkmcnt(6)
	v_mfma_f32_32x32x16_bf16 v[64:79], v[242:245], v[140:143], v[64:79]
	ds_read_b64_tr_b16 v[226:227], v185 offset:12288
	ds_read_b64_tr_b16 v[228:229], v185 offset:14336
	s_waitcnt lgkmcnt(6)
	v_mfma_f32_32x32x16_bf16 v[0:15], v[144:147], v[214:217], v[0:15]
	ds_read_b64_tr_b16 v[214:215], v185 offset:512
	ds_read_b64_tr_b16 v[216:217], v185 offset:2560
	s_waitcnt lgkmcnt(6)
	v_mfma_f32_32x32x16_bf16 v[0:15], v[148:151], v[218:221], v[0:15]
	ds_read_b64_tr_b16 v[218:219], v185 offset:4608
	ds_read_b64_tr_b16 v[220:221], v185 offset:6656
	s_waitcnt lgkmcnt(6)
	v_mfma_f32_32x32x16_bf16 v[0:15], v[152:155], v[222:225], v[0:15]
	ds_read_b64_tr_b16 v[222:223], v185 offset:8704
	ds_read_b64_tr_b16 v[224:225], v185 offset:10752
	s_waitcnt lgkmcnt(6)
	v_mfma_f32_32x32x16_bf16 v[0:15], v[156:159], v[226:229], v[0:15]
	ds_read_b64_tr_b16 v[226:227], v185 offset:12800
	ds_read_b64_tr_b16 v[228:229], v185 offset:14848
	s_waitcnt lgkmcnt(6)
	v_mfma_f32_32x32x16_bf16 v[48:63], v[144:147], v[214:217], v[48:63]
	ds_read_b64_tr_b16 v[214:215], v185 offset:1024
	ds_read_b64_tr_b16 v[216:217], v185 offset:3072
	v_max3_f32 v249, v249, v64, v65
	v_max3_f32 v249, v249, v66, v67
	v_max3_f32 v249, v249, v68, v69
	v_max3_f32 v249, v249, v70, v71
	v_max3_f32 v249, v249, v72, v73
	v_max3_f32 v249, v249, v74, v75
	v_max3_f32 v249, v249, v76, v77
	v_max3_f32 v249, v249, v78, v79
	s_waitcnt lgkmcnt(6)
	v_mfma_f32_32x32x16_bf16 v[48:63], v[148:151], v[218:221], v[48:63]
	ds_read_b64_tr_b16 v[218:219], v185 offset:5120
	ds_read_b64_tr_b16 v[220:221], v185 offset:7168
	v_mov_b32_e32 v250, v249
	s_nop 1
	v_permlane32_swap_b32_e32 v249, v250
	v_max_f32_e32 v249, v249, v250
	v_sub_f32_e32 v250, v249, v208
	v_cmp_ge_f32_e32 vcc, s40, v250
	v_max_f32_e32 v249, v208, v249
	v_sub_f32_e32 v250, v208, v249
	s_waitcnt lgkmcnt(6)
	v_mfma_f32_32x32x16_bf16 v[48:63], v[152:155], v[222:225], v[48:63]
	ds_read_b64_tr_b16 v[222:223], v185 offset:9216
	ds_read_b64_tr_b16 v[224:225], v185 offset:11264
	v_mul_f32_e32 v250, 0x3dd53b94, v250
	v_exp_f32_e32 v250, v250
	s_cmp_eq_u64 vcc, exec
	s_cselect_b64 s[10:11], -1, 0
	v_cndmask_b32_e64 v207, v250, 1.0, s[10:11]
	v_cndmask_b32_e64 v208, v249, v208, s[10:11]
	v_mul_f32_e32 v251, 0xbdd53b94, v208
	v_fmamk_f32 v80, v80, 0x3dd53b94, v251
	s_waitcnt lgkmcnt(6)
	v_mfma_f32_32x32x16_bf16 v[48:63], v[156:159], v[226:229], v[48:63]
	ds_read_b64_tr_b16 v[226:227], v185 offset:13312
	ds_read_b64_tr_b16 v[228:229], v185 offset:15360
	v_fmamk_f32 v81, v81, 0x3dd53b94, v251
	v_fmamk_f32 v82, v82, 0x3dd53b94, v251
	v_fmamk_f32 v83, v83, 0x3dd53b94, v251
	v_fmamk_f32 v84, v84, 0x3dd53b94, v251
	v_fmamk_f32 v85, v85, 0x3dd53b94, v251
	v_fmamk_f32 v86, v86, 0x3dd53b94, v251
	v_fmamk_f32 v87, v87, 0x3dd53b94, v251
	s_waitcnt lgkmcnt(6)
	v_mfma_f32_32x32x16_bf16 v[32:47], v[144:147], v[214:217], v[32:47]
	ds_read_b64_tr_b16 v[214:215], v185 offset:1536
	ds_read_b64_tr_b16 v[216:217], v185 offset:3584
	v_fmamk_f32 v88, v88, 0x3dd53b94, v251
	v_fmamk_f32 v89, v89, 0x3dd53b94, v251
	v_fmamk_f32 v90, v90, 0x3dd53b94, v251
	v_fmamk_f32 v91, v91, 0x3dd53b94, v251
	v_fmamk_f32 v92, v92, 0x3dd53b94, v251
	v_fmamk_f32 v93, v93, 0x3dd53b94, v251
	v_fmamk_f32 v94, v94, 0x3dd53b94, v251
	s_waitcnt lgkmcnt(6)
	v_mfma_f32_32x32x16_bf16 v[32:47], v[148:151], v[218:221], v[32:47]
	ds_read_b64_tr_b16 v[218:219], v185 offset:5632
	ds_read_b64_tr_b16 v[220:221], v185 offset:7680
	v_fmamk_f32 v95, v95, 0x3dd53b94, v251
	v_exp_f32_e32 v80, v80
	v_fmamk_f32 v64, v64, 0x3dd53b94, v251
	v_exp_f32_e32 v81, v81
	v_fmamk_f32 v65, v65, 0x3dd53b94, v251
	v_add_f32_e32 v212, 0, v80
	v_exp_f32_e32 v82, v82
	s_waitcnt lgkmcnt(6)
	v_mfma_f32_32x32x16_bf16 v[32:47], v[152:155], v[222:225], v[32:47]
	ds_read_b64_tr_b16 v[222:223], v185 offset:9728
	ds_read_b64_tr_b16 v[224:225], v185 offset:11776
	v_fmamk_f32 v66, v66, 0x3dd53b94, v251
	v_add_f32_e32 v212, v81, v212
	v_exp_f32_e32 v83, v83
	v_fmamk_f32 v67, v67, 0x3dd53b94, v251
	v_add_f32_e32 v212, v82, v212
	v_exp_f32_e32 v84, v84
	v_fmamk_f32 v68, v68, 0x3dd53b94, v251
	s_waitcnt lgkmcnt(6)
	v_mfma_f32_32x32x16_bf16 v[32:47], v[156:159], v[226:229], v[32:47]
	ds_read_b64_tr_b16 v[226:227], v185 offset:13824
	ds_read_b64_tr_b16 v[228:229], v185 offset:15872
	v_add_f32_e32 v212, v83, v212
	v_exp_f32_e32 v85, v85
	v_fmamk_f32 v69, v69, 0x3dd53b94, v251
	v_add_f32_e32 v212, v84, v212
	v_exp_f32_e32 v86, v86
	v_fmamk_f32 v70, v70, 0x3dd53b94, v251
	v_add_f32_e32 v212, v85, v212
	s_waitcnt lgkmcnt(6)
	v_mfma_f32_32x32x16_bf16 v[16:31], v[144:147], v[214:217], v[16:31]
	v_exp_f32_e32 v87, v87
	v_fmamk_f32 v71, v71, 0x3dd53b94, v251
	v_add_f32_e32 v212, v86, v212
	v_exp_f32_e32 v88, v88
	v_fmamk_f32 v72, v72, 0x3dd53b94, v251
	v_add_f32_e32 v212, v87, v212
	v_exp_f32_e32 v89, v89
	s_waitcnt lgkmcnt(4)
	v_mfma_f32_32x32x16_bf16 v[16:31], v[148:151], v[218:221], v[16:31]
	v_fmamk_f32 v73, v73, 0x3dd53b94, v251
	v_add_f32_e32 v212, v88, v212
	v_exp_f32_e32 v90, v90
	v_fmamk_f32 v74, v74, 0x3dd53b94, v251
	v_add_f32_e32 v212, v89, v212
	v_exp_f32_e32 v91, v91
	v_fmamk_f32 v75, v75, 0x3dd53b94, v251
	s_waitcnt lgkmcnt(2)
	v_mfma_f32_32x32x16_bf16 v[16:31], v[152:155], v[222:225], v[16:31]
	v_add_f32_e32 v212, v90, v212
	v_exp_f32_e32 v92, v92
	v_fmamk_f32 v76, v76, 0x3dd53b94, v251
	v_add_f32_e32 v212, v91, v212
	v_exp_f32_e32 v93, v93
	v_fmamk_f32 v77, v77, 0x3dd53b94, v251
	v_add_f32_e32 v212, v92, v212
	s_waitcnt lgkmcnt(0)
	v_mfma_f32_32x32x16_bf16 v[16:31], v[156:159], v[226:229], v[16:31]
	v_exp_f32_e32 v94, v94
	v_fmamk_f32 v78, v78, 0x3dd53b94, v251
	v_add_f32_e32 v212, v93, v212
	v_exp_f32_e32 v95, v95
	v_fmamk_f32 v79, v79, 0x3dd53b94, v251
	v_add_f32_e32 v212, v94, v212
	v_add_f32_e32 v212, v95, v212
	v_cvt_pk_bf16_f32 v144, v80, v81
	v_cvt_pk_bf16_f32 v145, v82, v83
	v_cvt_pk_bf16_f32 v146, v84, v85
	v_cvt_pk_bf16_f32 v147, v86, v87
	v_cvt_pk_bf16_f32 v148, v88, v89
	v_cvt_pk_bf16_f32 v149, v90, v91
	v_cvt_pk_bf16_f32 v150, v92, v93
	v_cvt_pk_bf16_f32 v151, v94, v95
	v_permlane32_swap_b32_e32 v144, v146
	v_permlane32_swap_b32_e32 v145, v147
	v_permlane32_swap_b32_e32 v148, v150
	v_permlane32_swap_b32_e32 v149, v151
	v_cmp_gt_f32_e32 vcc, 1.0, v207
	s_cbranch_vccz .Lmla_noresc_t
	s_and_saveexec_b64 s[0:1], s[8:9]
	ds_write_b32 v182, v207 offset:128
	s_or_b64 exec, exec, s[0:1]
	s_waitcnt lgkmcnt(0)
	v_add_u32_e32 v253, s50, v181
	ds_read_b128 v[92:95], v253 offset:224
	ds_read_b128 v[88:91], v253 offset:192
	ds_read_b128 v[84:87], v253 offset:160
	ds_read_b128 v[80:83], v253 offset:128
	s_waitcnt lgkmcnt(3)
	v_pk_mul_f32 v[12:13], v[12:13], v[92:93]
	v_pk_mul_f32 v[14:15], v[14:15], v[94:95]
	v_pk_mul_f32 v[60:61], v[60:61], v[92:93]
	v_pk_mul_f32 v[62:63], v[62:63], v[94:95]
	v_pk_mul_f32 v[44:45], v[44:45], v[92:93]
	v_pk_mul_f32 v[46:47], v[46:47], v[94:95]
	v_pk_mul_f32 v[28:29], v[28:29], v[92:93]
	v_pk_mul_f32 v[30:31], v[30:31], v[94:95]
	s_waitcnt lgkmcnt(2)
	v_pk_mul_f32 v[8:9], v[8:9], v[88:89]
	v_pk_mul_f32 v[10:11], v[10:11], v[90:91]
	v_pk_mul_f32 v[56:57], v[56:57], v[88:89]
	v_pk_mul_f32 v[58:59], v[58:59], v[90:91]
	v_pk_mul_f32 v[40:41], v[40:41], v[88:89]
	v_pk_mul_f32 v[42:43], v[42:43], v[90:91]
	v_pk_mul_f32 v[24:25], v[24:25], v[88:89]
	v_pk_mul_f32 v[26:27], v[26:27], v[90:91]
	s_waitcnt lgkmcnt(1)
	v_pk_mul_f32 v[4:5], v[4:5], v[84:85]
	v_pk_mul_f32 v[6:7], v[6:7], v[86:87]
	v_pk_mul_f32 v[52:53], v[52:53], v[84:85]
	v_pk_mul_f32 v[54:55], v[54:55], v[86:87]
	v_pk_mul_f32 v[36:37], v[36:37], v[84:85]
	v_pk_mul_f32 v[38:39], v[38:39], v[86:87]
	v_pk_mul_f32 v[20:21], v[20:21], v[84:85]
	v_pk_mul_f32 v[22:23], v[22:23], v[86:87]
	s_waitcnt lgkmcnt(0)
	v_pk_mul_f32 v[0:1], v[0:1], v[80:81]
	v_pk_mul_f32 v[2:3], v[2:3], v[82:83]
	v_pk_mul_f32 v[48:49], v[48:49], v[80:81]
	v_pk_mul_f32 v[50:51], v[50:51], v[82:83]
	v_pk_mul_f32 v[32:33], v[32:33], v[80:81]
	v_pk_mul_f32 v[34:35], v[34:35], v[82:83]
	v_pk_mul_f32 v[16:17], v[16:17], v[80:81]
	v_pk_mul_f32 v[18:19], v[18:19], v[82:83]
